# plus K-cache f32 to bf16 conversion loops (prologue and w_down phase) batched four loads in flight instead of load-wait-store per 16 bytes
# baseline (speedup 1.0000x reference)
.LBB0_114:
	s_mov_b64 s[10:11], s[88:89]
	s_mov_b64 s[0:1], s[88:89]
	s_load_dwordx2 s[4:5], s[0:1], 0x18
	s_waitcnt lgkmcnt(0)
	v_lshl_add_u32 v4, s91, 9, v76
	v_ashrrev_i32_e32 v5, 31, v4
	v_lshlrev_b64 v[2:3], 2, v[4:5]
	s_mov_b64 s[0:1], 0x800000
	v_cmp_gt_u64_e32 vcc, s[0:1], v[2:3]
	s_and_saveexec_b64 s[8:9], vcc
	s_cbranch_execz .LBB0_117
	s_load_dwordx2 s[0:1], s[10:11], 0x10
	s_add_u32 s10, s6, 0x1b200000
	s_addc_u32 s11, s7, 0
	s_ashr_i32 s15, s94, 31
	s_mov_b32 s14, s94
	s_lshl_b64 s[12:13], s[14:15], 11
	s_waitcnt lgkmcnt(0)
	v_lshl_add_u64 v[4:5], v[4:5], 4, s[0:1]
	s_lshl_b64 s[14:15], s[14:15], 13
	s_mov_b64 s[16:17], 0
	s_movk_i32 s0, 0x3fe0
	v_mov_b32_e32 v7, 0
	s_mov_b64 s[18:19], 0x7fffff
	s_lshl_b64 s[98:99], s[12:13], 1
	s_add_u32 s98, s98, s12
	s_addc_u32 s99, s99, s13
	s_mov_b64 s[100:101], exec
	v_mov_b32_e32 v121, 0
.Lkc0_main:
	v_lshl_add_u64 v[112:113], v[2:3], 0, s[98:99]
	v_cmp_ge_u64_e32 vcc, s[18:19], v[112:113]
	s_nop 1
	s_and_b64 exec, s[100:101], vcc
	s_cbranch_execz .Lkc0_rem
	global_load_dwordx4 v[96:99], v[4:5], off
	v_lshl_add_u64 v[4:5], v[4:5], 0, s[14:15]
	global_load_dwordx4 v[100:103], v[4:5], off
	v_lshl_add_u64 v[4:5], v[4:5], 0, s[14:15]
	global_load_dwordx4 v[104:107], v[4:5], off
	v_lshl_add_u64 v[4:5], v[4:5], 0, s[14:15]
	global_load_dwordx4 v[108:111], v[4:5], off
	v_lshl_add_u64 v[4:5], v[4:5], 0, s[14:15]
	s_waitcnt vmcnt(0)
	v_alignbit_b32 v116, v3, v2, 4
	v_lshrrev_b32_e32 v117, 9, v2
	v_and_b32_e32 v120, 31, v116
	v_and_or_b32 v117, v117, s0, v120
	v_lshlrev_b32_e32 v120, 10, v117
	v_and_b32_e32 v118, 12, v2
	v_lshl_add_u64 v[114:115], s[10:11], 0, v[120:121]
	v_and_b32_e32 v120, 0x3e0, v116
	v_lshl_add_u64 v[114:115], v[114:115], 0, v[120:121]
	v_lshlrev_b32_e32 v120, 1, v118
	v_lshl_add_u64 v[114:115], v[114:115], 0, v[120:121]
	v_cvt_pk_bf16_f32 v96, v96, v97
	v_cvt_pk_bf16_f32 v97, v98, v99
	global_store_dwordx2 v[114:115], v[96:97], off
	v_lshl_add_u64 v[2:3], v[2:3], 0, s[12:13]
	v_alignbit_b32 v116, v3, v2, 4
	v_lshrrev_b32_e32 v117, 9, v2
	v_and_b32_e32 v120, 31, v116
	v_and_or_b32 v117, v117, s0, v120
	v_lshlrev_b32_e32 v120, 10, v117
	v_and_b32_e32 v118, 12, v2
	v_lshl_add_u64 v[114:115], s[10:11], 0, v[120:121]
	v_and_b32_e32 v120, 0x3e0, v116
	v_lshl_add_u64 v[114:115], v[114:115], 0, v[120:121]
	v_lshlrev_b32_e32 v120, 1, v118
	v_lshl_add_u64 v[114:115], v[114:115], 0, v[120:121]
	v_cvt_pk_bf16_f32 v100, v100, v101
	v_cvt_pk_bf16_f32 v101, v102, v103
	global_store_dwordx2 v[114:115], v[100:101], off
	v_lshl_add_u64 v[2:3], v[2:3], 0, s[12:13]
	v_alignbit_b32 v116, v3, v2, 4
	v_lshrrev_b32_e32 v117, 9, v2
	v_and_b32_e32 v120, 31, v116
	v_and_or_b32 v117, v117, s0, v120
	v_lshlrev_b32_e32 v120, 10, v117
	v_and_b32_e32 v118, 12, v2
	v_lshl_add_u64 v[114:115], s[10:11], 0, v[120:121]
	v_and_b32_e32 v120, 0x3e0, v116
	v_lshl_add_u64 v[114:115], v[114:115], 0, v[120:121]
	v_lshlrev_b32_e32 v120, 1, v118
	v_lshl_add_u64 v[114:115], v[114:115], 0, v[120:121]
	v_cvt_pk_bf16_f32 v104, v104, v105
	v_cvt_pk_bf16_f32 v105, v106, v107
	global_store_dwordx2 v[114:115], v[104:105], off
	v_lshl_add_u64 v[2:3], v[2:3], 0, s[12:13]
	v_alignbit_b32 v116, v3, v2, 4
	v_lshrrev_b32_e32 v117, 9, v2
	v_and_b32_e32 v120, 31, v116
	v_and_or_b32 v117, v117, s0, v120
	v_lshlrev_b32_e32 v120, 10, v117
	v_and_b32_e32 v118, 12, v2
	v_lshl_add_u64 v[114:115], s[10:11], 0, v[120:121]
	v_and_b32_e32 v120, 0x3e0, v116
	v_lshl_add_u64 v[114:115], v[114:115], 0, v[120:121]
	v_lshlrev_b32_e32 v120, 1, v118
	v_lshl_add_u64 v[114:115], v[114:115], 0, v[120:121]
	v_cvt_pk_bf16_f32 v108, v108, v109
	v_cvt_pk_bf16_f32 v109, v110, v111
	global_store_dwordx2 v[114:115], v[108:109], off
	v_lshl_add_u64 v[2:3], v[2:3], 0, s[12:13]
	s_branch .Lkc0_main
.Lkc0_rem:
	s_mov_b64 exec, s[100:101]
	v_cmp_ge_u64_e32 vcc, s[18:19], v[2:3]
	s_nop 1
	s_and_b64 exec, exec, vcc
	s_cbranch_execz .LBB0_117

; __global__ void __launch_bounds__(512, 2) fwd_mega(Args args) {
;     ...
;             { int bxo = blockIdx.x; asm volatile("" : "+s"(bxo)); if (l + 1 < DEPTH && bxo >= 16) { CACHE_CONVERT(l + 1, bxo - 16, G - 16); } }
.LBB0_1015:
	s_add_i32 s0, s96, 1
	s_mov_b32 s1, s91
	s_cmp_lg_u32 s96, 3
	s_cselect_b64 s[4:5], -1, 0
	s_cmp_gt_i32 s1, 15
	s_cselect_b64 s[6:7], -1, 0
	s_and_b64 s[4:5], s[4:5], s[6:7]
	v_readlane_b32 s30, v255, 19
	v_readlane_b32 s16, v255, 4
	s_andn2_b64 vcc, exec, s[4:5]
	v_readlane_b32 s31, v255, 20
	v_readlane_b32 s17, v255, 5
	s_cbranch_vccnz .LBB0_1024
	s_mov_b64 s[8:9], s[88:89]
	s_mov_b64 s[4:5], s[88:89]
	s_load_dwordx2 s[4:5], s[4:5], 0x18
	s_add_i32 s1, s1, -16
	v_lshl_add_u32 v2, s1, 9, v144
	v_ashrrev_i32_e32 v3, 31, v2
	s_waitcnt lgkmcnt(0)
	v_lshlrev_b64 v[0:1], 2, v[2:3]
	s_mov_b64 s[6:7], 0x800000
	v_cmp_gt_u64_e32 vcc, s[6:7], v[0:1]
	s_and_saveexec_b64 s[6:7], vcc
	s_cbranch_execz .LBB0_1019
	s_load_dwordx2 s[10:11], s[8:9], 0x10
	s_add_u32 s8, s2, 0x1b200000
	s_addc_u32 s9, s3, 0
	v_readlane_b32 s12, v255, 6
	v_readlane_b32 s13, v255, 7
	s_waitcnt lgkmcnt(0)
	s_add_u32 s10, s10, s12
	s_addc_u32 s11, s11, s13
	v_lshl_add_u64 v[2:3], v[2:3], 4, s[10:11]
	s_mov_b64 s[10:11], 0
	s_mov_b64 s[12:13], 0x7fffff
	s_movk_i32 s14, 0x3fe0
	s_lshl_b64 s[98:99], s[30:31], 1
	s_add_u32 s98, s98, s30
	s_addc_u32 s99, s99, s31
	s_mov_b64 s[100:101], exec
	v_mov_b32_e32 v253, 0
.Lkc1_main:
	v_lshl_add_u64 v[244:245], v[0:1], 0, s[98:99]
	v_cmp_ge_u64_e32 vcc, s[12:13], v[244:245]
	s_nop 1
	s_and_b64 exec, s[100:101], vcc
	s_cbranch_execz .Lkc1_rem
	global_load_dwordx4 v[228:231], v[2:3], off
	v_lshl_add_u64 v[2:3], v[2:3], 0, s[16:17]
	global_load_dwordx4 v[232:235], v[2:3], off
	v_lshl_add_u64 v[2:3], v[2:3], 0, s[16:17]
	global_load_dwordx4 v[236:239], v[2:3], off
	v_lshl_add_u64 v[2:3], v[2:3], 0, s[16:17]
	global_load_dwordx4 v[240:243], v[2:3], off
	v_lshl_add_u64 v[2:3], v[2:3], 0, s[16:17]
	s_waitcnt vmcnt(0)
	v_alignbit_b32 v248, v1, v0, 4
	v_lshrrev_b32_e32 v249, 9, v0
	v_and_b32_e32 v252, 31, v248
	v_and_or_b32 v249, v249, s14, v252
	v_lshlrev_b32_e32 v252, 10, v249
	v_and_b32_e32 v250, 12, v0
	v_lshl_add_u64 v[246:247], s[8:9], 0, v[252:253]
	v_and_b32_e32 v252, 0x3e0, v248
	v_lshl_add_u64 v[246:247], v[246:247], 0, v[252:253]
	v_lshlrev_b32_e32 v252, 1, v250
	v_lshl_add_u64 v[246:247], v[246:247], 0, v[252:253]
	v_cvt_pk_bf16_f32 v228, v228, v229
	v_cvt_pk_bf16_f32 v229, v230, v231
	global_store_dwordx2 v[246:247], v[228:229], off
	v_lshl_add_u64 v[0:1], v[0:1], 0, s[30:31]
	v_alignbit_b32 v248, v1, v0, 4
	v_lshrrev_b32_e32 v249, 9, v0
	v_and_b32_e32 v252, 31, v248
	v_and_or_b32 v249, v249, s14, v252
	v_lshlrev_b32_e32 v252, 10, v249
	v_and_b32_e32 v250, 12, v0
	v_lshl_add_u64 v[246:247], s[8:9], 0, v[252:253]
	v_and_b32_e32 v252, 0x3e0, v248
	v_lshl_add_u64 v[246:247], v[246:247], 0, v[252:253]
	v_lshlrev_b32_e32 v252, 1, v250
	v_lshl_add_u64 v[246:247], v[246:247], 0, v[252:253]
	v_cvt_pk_bf16_f32 v232, v232, v233
	v_cvt_pk_bf16_f32 v233, v234, v235
	global_store_dwordx2 v[246:247], v[232:233], off
	v_lshl_add_u64 v[0:1], v[0:1], 0, s[30:31]
	v_alignbit_b32 v248, v1, v0, 4
	v_lshrrev_b32_e32 v249, 9, v0
	v_and_b32_e32 v252, 31, v248
	v_and_or_b32 v249, v249, s14, v252
	v_lshlrev_b32_e32 v252, 10, v249
	v_and_b32_e32 v250, 12, v0
	v_lshl_add_u64 v[246:247], s[8:9], 0, v[252:253]
	v_and_b32_e32 v252, 0x3e0, v248
	v_lshl_add_u64 v[246:247], v[246:247], 0, v[252:253]
	v_lshlrev_b32_e32 v252, 1, v250
	v_lshl_add_u64 v[246:247], v[246:247], 0, v[252:253]
	v_cvt_pk_bf16_f32 v236, v236, v237
	v_cvt_pk_bf16_f32 v237, v238, v239
	global_store_dwordx2 v[246:247], v[236:237], off
	v_lshl_add_u64 v[0:1], v[0:1], 0, s[30:31]
	v_alignbit_b32 v248, v1, v0, 4
	v_lshrrev_b32_e32 v249, 9, v0
	v_and_b32_e32 v252, 31, v248
	v_and_or_b32 v249, v249, s14, v252
	v_lshlrev_b32_e32 v252, 10, v249
	v_and_b32_e32 v250, 12, v0
	v_lshl_add_u64 v[246:247], s[8:9], 0, v[252:253]
	v_and_b32_e32 v252, 0x3e0, v248
	v_lshl_add_u64 v[246:247], v[246:247], 0, v[252:253]
	v_lshlrev_b32_e32 v252, 1, v250
	v_lshl_add_u64 v[246:247], v[246:247], 0, v[252:253]
	v_cvt_pk_bf16_f32 v240, v240, v241
	v_cvt_pk_bf16_f32 v241, v242, v243
	global_store_dwordx2 v[246:247], v[240:241], off
	v_lshl_add_u64 v[0:1], v[0:1], 0, s[30:31]
	s_branch .Lkc1_main
.Lkc1_rem:
	s_mov_b64 exec, s[100:101]
	v_cmp_ge_u64_e32 vcc, s[12:13], v[0:1]
	s_nop 1
	s_and_b64 exec, exec, vcc
	s_cbranch_execz .LBB0_1019
